# grid barrier: the XCD leader releases its XCD before invalidating its own caches
# speedup vs baseline: 1.0078x; 1.0078x over previous
; __device__ __forceinline__ unsigned xb_ld(unsigned* p)              { return __hip_atomic_load(p, __ATOMIC_RELAXED, __HIP_MEMORY_SCOPE_AGENT); }
; __device__ __forceinline__ unsigned xb_add(unsigned* p, unsigned v) { return __hip_atomic_fetch_add(p, v, __ATOMIC_RELAXED, __HIP_MEMORY_SCOPE_AGENT); }
; #define XB_SPIN(cond, bar) do { unsigned _sp = 0; while (cond) { __builtin_amdgcn_s_sleep(1); \
;     if ((++_sp & 255u) == 0u) { if (xb_ld(&(bar)[XB_TMO])) break; if (_sp > XB_SPIN_CAP) { atomicAdd(&(bar)[XB_TMO], 1u); break; } } } } while (0)
; __device__ __forceinline__ void xcd_barrier(const XcdBarrier& b) {
;     ...
;             __builtin_amdgcn_fence(__ATOMIC_RELEASE, "agent");
;             asm volatile("s_waitcnt vmcnt(0)" ::: "memory");
;             const unsigned og = xb_add(&bar[XB_TOP], 1u);
;             const unsigned tg = og / nx;
;             if (og + 1u == (tg + 1u) * nx) xb_add(&bar[XB_TOPGEN], 1u);
;             else XB_SPIN(xb_ld(&bar[XB_TOPGEN]) == tg, bar);
;             __builtin_amdgcn_fence(__ATOMIC_ACQUIRE, "agent");
;             xb_add(&bar[XB_XGEN(b.x)], 1u);
;             asm volatile("s_waitcnt vmcnt(0)" ::: "memory");
.LBB0_2002:
	s_or_b64 exec, exec, s[4:5]
	s_add_i32 s56, s24, 0x900
	s_lshl_b64 s[4:5], s[56:57], 2
	s_add_u32 s2, s2, s4
	s_addc_u32 s3, s3, s5
	v_mov_b64_e32 v[0:1], s[2:3]
	v_mov_b32_e32 v2, 1
	s_waitcnt vmcnt(0) lgkmcnt(0)
	flat_atomic_add v[0:1], v2
	buffer_inv sc1
	s_waitcnt vmcnt(0)
